# mixer B loop v2: rotated pipeline, linear ALiBi bias chain for tiles away from the diagonal (general form kept for the diagonal iteration), K/V staging write moved half an iteration later
# speedup vs baseline: 1.0085x; 1.0079x over previous
; #define LAS __attribute__((address_space(3)))
; DI float alibi_c(float dkf, float pf, float nslope2, float nbound) { float t, c;
;     asm("v_add_f32_e32 %0, %1, %2" : "=v"(t) : "s"(dkf), "v"(pf));
;     asm("v_fma_f32 %0, |%1|, %2, %3" : "=v"(c) : "v"(t), "s"(nslope2), "v"(nbound));
;     return c; }
; DI void mixerB2_unit(int u, int l, const bf16* PROJ, bf16* YC, const float* dlam_l, const float* dnw_l, const float* kmax_l, LAS char* lds, int tid, int wave, int lane) {
;     ...
;     for (int kt128 = 0; kt128 < 16; ++kt128) {
;         {
;         const LAS char* K0 = Kb + (kt128 & 1) * KV_TILE; const LAS char* V0 = Vb + (kt128 & 1) * KV_TILE;
;     ...
;         SBlk SA, SB;
;         B_QK(SA, 0, 0); B_QK(SB, 0, 1);
;         B_SMPV(SA, 0, 0);
;         if (kt128 + 1 < 16) { const size_t ro = (size_t)(128 * (kt128 + 1) + lrow) * 64 + lch * 8; rk = *(const u32x4*)(kbase + ro); rv = *(const u32x4*)(vbase + ro); }
;         B_QK(SA, 1, 0);
;         B_SMPV(SB, 0, 1);
;         B_QK(SB, 1, 1);
.LBB0_254:
	s_mov_b32 s0, 0
	s_movk_i32 s1, 0x4800
	v_add_u32_e32 v232, v171, v166
	v_add_u32_e32 v250, v198, v199
	v_mov_b32_e32 v218, v232
	v_mov_b32_e32 v217, v250
	ds_read_b128 v[156:159], v213
	ds_read_b128 v[160:163], v213 offset:64
	ds_read_b128 v[242:245], v213 offset:2304
	ds_read_b128 v[246:249], v213 offset:2368
	ds_read_b128 v[140:143], v218
	ds_read_b128 v[144:147], v218 offset:64
	ds_read_b128 v[148:151], v218 offset:2304
	ds_read_b128 v[152:155], v218 offset:2368
	v_mov_b32_e32 v228, 0x3f803f80
	v_mov_b32_e32 v229, 0x3f803f80
	v_mov_b32_e32 v230, 0x3f803f80
	v_mov_b32_e32 v231, 0x3f803f80
	v_mov_b32_e32 v116, 0
	v_mov_b32_e32 v117, 0
	v_mov_b32_e32 v118, 0
	v_mov_b32_e32 v119, 0
	v_mov_b32_e32 v120, 0
	v_mov_b32_e32 v121, 0
	v_mov_b32_e32 v122, 0
	v_mov_b32_e32 v123, 0
	v_mov_b32_e32 v124, 0
	v_mov_b32_e32 v125, 0
	v_mov_b32_e32 v126, 0
	v_mov_b32_e32 v127, 0
	v_mov_b32_e32 v128, 0
	v_mov_b32_e32 v129, 0
	v_mov_b32_e32 v130, 0
	v_mov_b32_e32 v131, 0
	v_mov_b32_e32 v132, 0
	v_mov_b32_e32 v133, 0
	v_mov_b32_e32 v134, 0
	v_mov_b32_e32 v135, 0
	v_mov_b32_e32 v136, 0
	v_mov_b32_e32 v137, 0
	v_mov_b32_e32 v138, 0
	v_mov_b32_e32 v139, 0
	s_add_i32 s40, s44, s46
	s_waitcnt lgkmcnt(4)
.Lb2_top:
	s_add_i32 s41, s40, 0x60
	s_cmp_le_u32 s41, 0x60
	s_cbranch_scc1 .Lb2_near
	s_cmp_ge_i32 s40, 0
	s_cselect_b32 s41, 0, 0x80000000
	v_xor_b32_e32 v251, s41, v214
	v_mul_f32_e32 v225, 0x41800000, v251
	s_sub_i32 s41, s40, 0
	v_cvt_f32_i32_e32 v219, s41
	v_add_f32_e32 v194, v219, v186
	v_add_f32_e32 v195, v219, v187
	v_add_f32_e32 v196, v219, v191
	v_add_f32_e32 v197, v219, v193
	v_fma_f32 v194, v194, v251, v215
	v_fma_f32 v195, v195, v251, v215
	v_fma_f32 v196, v196, v251, v215
	v_fma_f32 v197, v197, v251, v215
	s_nop 1
	s_waitcnt lgkmcnt(3)
	v_mfma_f32_16x16x32_bf16 v[92:95], v[140:143], v[156:159], v[194:197]
	s_waitcnt lgkmcnt(2)
	v_mfma_f32_16x16x32_bf16 v[96:99], v[144:147], v[160:163], v[194:197]
	s_nop 2
	v_add_f32_e32 v194, v225, v194
	v_add_f32_e32 v195, v225, v195
	v_add_f32_e32 v196, v225, v196
	v_add_f32_e32 v197, v225, v197
	s_nop 1
	s_waitcnt lgkmcnt(1)
	v_mfma_f32_16x16x32_bf16 v[100:103], v[148:151], v[156:159], v[194:197]
	s_waitcnt lgkmcnt(0)
	v_mfma_f32_16x16x32_bf16 v[104:107], v[152:155], v[160:163], v[194:197]
	s_nop 2
	v_add_f32_e32 v194, v225, v194
	v_add_f32_e32 v195, v225, v195
	v_add_f32_e32 v196, v225, v196
	v_add_f32_e32 v197, v225, v197
	v_mfma_f32_16x16x32_bf16 v[52:55], v[228:231], v[116:119], v[52:55]
	v_exp_f32_e32 v92, v92
	v_exp_f32_e32 v93, v93
	v_mfma_f32_16x16x32_bf16 v[48:51], v[228:231], v[120:123], v[48:51]
	v_exp_f32_e32 v94, v94
	v_exp_f32_e32 v95, v95
	v_mfma_f32_16x16x32_bf16 v[44:47], v[124:127], v[116:119], v[44:47]
	v_exp_f32_e32 v100, v100
	v_exp_f32_e32 v101, v101
	v_mfma_f32_16x16x32_bf16 v[32:35], v[124:127], v[120:123], v[32:35]
	v_exp_f32_e32 v102, v102
	v_exp_f32_e32 v103, v103
	v_mfma_f32_16x16x32_bf16 v[40:43], v[128:131], v[116:119], v[40:43]
	v_cvt_pk_bf16_f32 v108, v92, v93
	v_cvt_pk_bf16_f32 v109, v94, v95
	v_cvt_pk_bf16_f32 v110, v100, v101
	v_mfma_f32_16x16x32_bf16 v[24:27], v[128:131], v[120:123], v[24:27]
	v_cvt_pk_bf16_f32 v111, v102, v103
	v_exp_f32_e32 v96, v96
	v_exp_f32_e32 v97, v97
	v_mfma_f32_16x16x32_bf16 v[36:39], v[132:135], v[116:119], v[36:39]
	v_exp_f32_e32 v98, v98
	v_exp_f32_e32 v99, v99
	v_mfma_f32_16x16x32_bf16 v[20:23], v[132:135], v[120:123], v[20:23]
	v_exp_f32_e32 v104, v104
	v_exp_f32_e32 v105, v105
	v_mfma_f32_16x16x32_bf16 v[28:31], v[136:139], v[116:119], v[28:31]
	v_exp_f32_e32 v106, v106
	v_exp_f32_e32 v107, v107
	v_mfma_f32_16x16x32_bf16 v[16:19], v[136:139], v[120:123], v[16:19]
	v_cvt_pk_bf16_f32 v112, v96, v97
	v_cvt_pk_bf16_f32 v113, v98, v99
	v_cvt_pk_bf16_f32 v114, v104, v105
	v_cvt_pk_bf16_f32 v115, v106, v107
	s_sub_i32 s41, s40, 16
	v_cvt_f32_i32_e32 v219, s41
	v_add_f32_e32 v220, v219, v186
	v_add_f32_e32 v221, v219, v187
	v_add_f32_e32 v222, v219, v191
	v_add_f32_e32 v223, v219, v193
	v_fma_f32 v220, v220, v251, v216
	v_fma_f32 v221, v221, v251, v216
	v_fma_f32 v222, v222, v251, v216
	v_fma_f32 v223, v223, v251, v216
	s_nop 1
	v_mfma_f32_16x16x32_bf16 v[92:95], v[140:143], v[242:245], v[220:223]
	v_mfma_f32_16x16x32_bf16 v[96:99], v[144:147], v[246:249], v[220:223]
	s_nop 2
	v_add_f32_e32 v220, v225, v220
	v_add_f32_e32 v221, v225, v221
	v_add_f32_e32 v222, v225, v222
	v_add_f32_e32 v223, v225, v223
	s_nop 1
	v_mfma_f32_16x16x32_bf16 v[100:103], v[148:151], v[242:245], v[220:223]
	v_mfma_f32_16x16x32_bf16 v[104:107], v[152:155], v[246:249], v[220:223]
	s_cmpk_eq_i32 s46, 0x780
	s_cbranch_scc1 .Lb2_skip1_f
	v_add_co_u32_e32 v4, vcc, 0xff7fe000, v180
	s_nop 1
	v_addc_co_u32_e32 v5, vcc, -1, v181, vcc
	v_add_co_u32_e32 v8, vcc, 0xffffe000, v180
	s_nop 1
	v_addc_co_u32_e32 v9, vcc, -1, v181, vcc
	global_load_dwordx4 v[4:7], v[4:5], off
	s_nop 0
	global_load_dwordx4 v[8:11], v[8:9], off
; DI float alibi_c(float dkf, float pf, float nslope2, float nbound) { float t, c;
;     asm("v_add_f32_e32 %0, %1, %2" : "=v"(t) : "s"(dkf), "v"(pf));
;     asm("v_fma_f32 %0, |%1|, %2, %3" : "=v"(c) : "v"(t), "s"(nslope2), "v"(nbound));
;     return c; }
; DI void mixerB2_unit(int u, int l, const bf16* PROJ, bf16* YC, const float* dlam_l, const float* dnw_l, const float* kmax_l, LAS char* lds, int tid, int wave, int lane) {
;     ...
;         SBlk SA, SB;
;         B_QK(SA, 0, 0); B_QK(SB, 0, 1);
;         B_SMPV(SA, 0, 0);
;         if (kt128 + 1 < 16) { const size_t ro = (size_t)(128 * (kt128 + 1) + lrow) * 64 + lch * 8; rk = *(const u32x4*)(kbase + ro); rv = *(const u32x4*)(vbase + ro); }
;         B_QK(SA, 1, 0);
;         B_SMPV(SB, 0, 1);
.Lb2_skip1_f:
	ds_read_b64_tr_b16 v[124:125], v217 offset:36864
	ds_read_b64_tr_b16 v[126:127], v217 offset:39168
	ds_read_b64_tr_b16 v[128:129], v217 offset:36896
	ds_read_b64_tr_b16 v[130:131], v217 offset:39200
	ds_read_b64_tr_b16 v[132:133], v217 offset:36928
	ds_read_b64_tr_b16 v[134:135], v217 offset:39232
	ds_read_b64_tr_b16 v[136:137], v217 offset:36960
	ds_read_b64_tr_b16 v[138:139], v217 offset:39264
	s_nop 2
	v_add_f32_e32 v220, v225, v220
	v_add_f32_e32 v221, v225, v221
	v_add_f32_e32 v222, v225, v222
	v_add_f32_e32 v223, v225, v223
	ds_read_b128 v[140:143], v218 offset:4608
	ds_read_b128 v[144:147], v218 offset:4672
	ds_read_b128 v[148:151], v218 offset:6912
	ds_read_b128 v[152:155], v218 offset:6976
	v_mfma_f32_16x16x32_bf16 v[88:91], v[228:231], v[108:111], v[88:91]
	v_exp_f32_e32 v92, v92
	v_exp_f32_e32 v93, v93
	v_mfma_f32_16x16x32_bf16 v[84:87], v[228:231], v[112:115], v[84:87]
	v_exp_f32_e32 v94, v94
	v_exp_f32_e32 v95, v95
	s_waitcnt lgkmcnt(10)
	v_mfma_f32_16x16x32_bf16 v[80:83], v[124:127], v[108:111], v[80:83]
	v_exp_f32_e32 v100, v100
	v_exp_f32_e32 v101, v101
	v_mfma_f32_16x16x32_bf16 v[12:15], v[124:127], v[112:115], v[12:15]
	v_exp_f32_e32 v102, v102
	v_exp_f32_e32 v103, v103
	s_waitcnt lgkmcnt(8)
	v_mfma_f32_16x16x32_bf16 v[76:79], v[128:131], v[108:111], v[76:79]
	v_cvt_pk_bf16_f32 v116, v92, v93
	v_cvt_pk_bf16_f32 v117, v94, v95
	v_cvt_pk_bf16_f32 v118, v100, v101
	v_mfma_f32_16x16x32_bf16 v[64:67], v[128:131], v[112:115], v[64:67]
	v_cvt_pk_bf16_f32 v119, v102, v103
	v_exp_f32_e32 v96, v96
	v_exp_f32_e32 v97, v97
	s_waitcnt lgkmcnt(6)
	v_mfma_f32_16x16x32_bf16 v[72:75], v[132:135], v[108:111], v[72:75]
	v_exp_f32_e32 v98, v98
	v_exp_f32_e32 v99, v99
	v_mfma_f32_16x16x32_bf16 v[60:63], v[132:135], v[112:115], v[60:63]
	v_exp_f32_e32 v104, v104
	v_exp_f32_e32 v105, v105
	s_waitcnt lgkmcnt(4)
	v_mfma_f32_16x16x32_bf16 v[68:71], v[136:139], v[108:111], v[68:71]
	v_exp_f32_e32 v106, v106
	v_exp_f32_e32 v107, v107
	v_mfma_f32_16x16x32_bf16 v[56:59], v[136:139], v[112:115], v[56:59]
	v_cvt_pk_bf16_f32 v120, v96, v97
	v_cvt_pk_bf16_f32 v121, v98, v99
	v_cvt_pk_bf16_f32 v122, v104, v105
	v_cvt_pk_bf16_f32 v123, v106, v107
	s_waitcnt lgkmcnt(3)
	v_mfma_f32_16x16x32_bf16 v[92:95], v[140:143], v[156:159], v[194:197]
	s_waitcnt lgkmcnt(2)
	v_mfma_f32_16x16x32_bf16 v[96:99], v[144:147], v[160:163], v[194:197]
	s_nop 2
	v_add_f32_e32 v194, v225, v194
	v_add_f32_e32 v195, v225, v195
	v_add_f32_e32 v196, v225, v196
	v_add_f32_e32 v197, v225, v197
	s_nop 1
	s_waitcnt lgkmcnt(1)
	v_mfma_f32_16x16x32_bf16 v[100:103], v[148:151], v[156:159], v[194:197]
	s_waitcnt lgkmcnt(0)
	v_mfma_f32_16x16x32_bf16 v[104:107], v[152:155], v[160:163], v[194:197]
	s_nop 2
	v_add_f32_e32 v194, v225, v194
	v_add_f32_e32 v195, v225, v195
	v_add_f32_e32 v196, v225, v196
	v_add_f32_e32 v197, v225, v197
	v_mfma_f32_16x16x32_bf16 v[52:55], v[228:231], v[116:119], v[52:55]
	v_exp_f32_e32 v92, v92
	v_exp_f32_e32 v93, v93
	v_mfma_f32_16x16x32_bf16 v[48:51], v[228:231], v[120:123], v[48:51]
	v_exp_f32_e32 v94, v94
	v_exp_f32_e32 v95, v95
	v_mfma_f32_16x16x32_bf16 v[44:47], v[124:127], v[116:119], v[44:47]
	v_exp_f32_e32 v100, v100
	v_exp_f32_e32 v101, v101
	v_mfma_f32_16x16x32_bf16 v[32:35], v[124:127], v[120:123], v[32:35]
	v_exp_f32_e32 v102, v102
	v_exp_f32_e32 v103, v103
	v_mfma_f32_16x16x32_bf16 v[40:43], v[128:131], v[116:119], v[40:43]
	v_cvt_pk_bf16_f32 v108, v92, v93
	v_cvt_pk_bf16_f32 v109, v94, v95
	v_cvt_pk_bf16_f32 v110, v100, v101
	v_mfma_f32_16x16x32_bf16 v[24:27], v[128:131], v[120:123], v[24:27]
	v_cvt_pk_bf16_f32 v111, v102, v103
	v_exp_f32_e32 v96, v96
	v_exp_f32_e32 v97, v97
	v_mfma_f32_16x16x32_bf16 v[36:39], v[132:135], v[116:119], v[36:39]
	v_exp_f32_e32 v98, v98
	v_exp_f32_e32 v99, v99
	v_mfma_f32_16x16x32_bf16 v[20:23], v[132:135], v[120:123], v[20:23]
	v_exp_f32_e32 v104, v104
	v_exp_f32_e32 v105, v105
	v_mfma_f32_16x16x32_bf16 v[28:31], v[136:139], v[116:119], v[28:31]
	v_exp_f32_e32 v106, v106
	v_exp_f32_e32 v107, v107
	v_mfma_f32_16x16x32_bf16 v[16:19], v[136:139], v[120:123], v[16:19]
	v_cvt_pk_bf16_f32 v112, v96, v97
	v_cvt_pk_bf16_f32 v113, v98, v99
	v_cvt_pk_bf16_f32 v114, v104, v105
	v_cvt_pk_bf16_f32 v115, v106, v107
	v_mfma_f32_16x16x32_bf16 v[92:95], v[140:143], v[242:245], v[220:223]
	v_mfma_f32_16x16x32_bf16 v[96:99], v[144:147], v[246:249], v[220:223]
	s_nop 2
	v_add_f32_e32 v220, v225, v220
	v_add_f32_e32 v221, v225, v221
	v_add_f32_e32 v222, v225, v222
	v_add_f32_e32 v223, v225, v223
	s_nop 1
	v_mfma_f32_16x16x32_bf16 v[100:103], v[148:151], v[242:245], v[220:223]
	v_mfma_f32_16x16x32_bf16 v[104:107], v[152:155], v[246:249], v[220:223]
	ds_read_b64_tr_b16 v[124:125], v217 offset:41472
	ds_read_b64_tr_b16 v[126:127], v217 offset:43776
	ds_read_b64_tr_b16 v[128:129], v217 offset:41504
	ds_read_b64_tr_b16 v[130:131], v217 offset:43808
	ds_read_b64_tr_b16 v[132:133], v217 offset:41536
	ds_read_b64_tr_b16 v[134:135], v217 offset:43840
	ds_read_b64_tr_b16 v[136:137], v217 offset:41568
	ds_read_b64_tr_b16 v[138:139], v217 offset:43872
	s_nop 2
	v_add_f32_e32 v220, v225, v220
	v_add_f32_e32 v221, v225, v221
	v_add_f32_e32 v222, v225, v222
	v_add_f32_e32 v223, v225, v223
	ds_read_b128 v[140:143], v218 offset:9216
	ds_read_b128 v[144:147], v218 offset:9280
	ds_read_b128 v[148:151], v218 offset:11520
	ds_read_b128 v[152:155], v218 offset:11584
	v_mfma_f32_16x16x32_bf16 v[88:91], v[228:231], v[108:111], v[88:91]
	v_exp_f32_e32 v92, v92
	v_exp_f32_e32 v93, v93
	v_mfma_f32_16x16x32_bf16 v[84:87], v[228:231], v[112:115], v[84:87]
	v_exp_f32_e32 v94, v94
	v_exp_f32_e32 v95, v95
	s_waitcnt lgkmcnt(10)
; #define LAS __attribute__((address_space(3)))
; DI void mixerB2_unit(int u, int l, const bf16* PROJ, bf16* YC, const float* dlam_l, const float* dnw_l, const float* kmax_l, LAS char* lds, int tid, int wave, int lane) {
;     ...
;         SBlk SA, SB;
;         B_QK(SA, 0, 0); B_QK(SB, 0, 1);
;         B_SMPV(SA, 0, 0);
;         if (kt128 + 1 < 16) { const size_t ro = (size_t)(128 * (kt128 + 1) + lrow) * 64 + lch * 8; rk = *(const u32x4*)(kbase + ro); rv = *(const u32x4*)(vbase + ro); }
;         B_QK(SA, 1, 0);
;         B_SMPV(SB, 0, 1);
;         B_QK(SB, 1, 1);
;         if (kt128 + 1 < 16) { LAS char* Kn = Kb + ((kt128 + 1) & 1) * KV_TILE; LAS char* Vn = Vb + ((kt128 + 1) & 1) * KV_TILE;
;             *(LAS u32x4*)(Kn + lrow * KV_PITCH + lch * 16) = rk; *(LAS u32x4*)(Vn + lrow * KV_PITCH + lch * 16) = rv;
;             const size_t ro = (size_t)(128 * (kt128 + 1) + 64 + lrow) * 64 + lch * 8; rk = *(const u32x4*)(kbase + ro); rv = *(const u32x4*)(vbase + ro); }
	v_mfma_f32_16x16x32_bf16 v[80:83], v[124:127], v[108:111], v[80:83]
	v_exp_f32_e32 v100, v100
	v_exp_f32_e32 v101, v101
	v_mfma_f32_16x16x32_bf16 v[12:15], v[124:127], v[112:115], v[12:15]
	v_exp_f32_e32 v102, v102
	v_exp_f32_e32 v103, v103
	s_waitcnt lgkmcnt(8)
	v_mfma_f32_16x16x32_bf16 v[76:79], v[128:131], v[108:111], v[76:79]
	v_cvt_pk_bf16_f32 v116, v92, v93
	v_cvt_pk_bf16_f32 v117, v94, v95
	v_cvt_pk_bf16_f32 v118, v100, v101
	v_mfma_f32_16x16x32_bf16 v[64:67], v[128:131], v[112:115], v[64:67]
	v_cvt_pk_bf16_f32 v119, v102, v103
	v_exp_f32_e32 v96, v96
	v_exp_f32_e32 v97, v97
	s_waitcnt lgkmcnt(6)
	v_mfma_f32_16x16x32_bf16 v[72:75], v[132:135], v[108:111], v[72:75]
	v_exp_f32_e32 v98, v98
	v_exp_f32_e32 v99, v99
	v_mfma_f32_16x16x32_bf16 v[60:63], v[132:135], v[112:115], v[60:63]
	v_exp_f32_e32 v104, v104
	v_exp_f32_e32 v105, v105
	s_waitcnt lgkmcnt(4)
	v_mfma_f32_16x16x32_bf16 v[68:71], v[136:139], v[108:111], v[68:71]
	v_exp_f32_e32 v106, v106
	v_exp_f32_e32 v107, v107
	v_mfma_f32_16x16x32_bf16 v[56:59], v[136:139], v[112:115], v[56:59]
	v_cvt_pk_bf16_f32 v120, v96, v97
	v_cvt_pk_bf16_f32 v121, v98, v99
	v_cvt_pk_bf16_f32 v122, v104, v105
	v_cvt_pk_bf16_f32 v123, v106, v107
	s_waitcnt lgkmcnt(3)
	v_mfma_f32_16x16x32_bf16 v[92:95], v[140:143], v[156:159], v[194:197]
	s_waitcnt lgkmcnt(2)
	v_mfma_f32_16x16x32_bf16 v[96:99], v[144:147], v[160:163], v[194:197]
	s_nop 2
	v_add_f32_e32 v194, v225, v194
	v_add_f32_e32 v195, v225, v195
	v_add_f32_e32 v196, v225, v196
	v_add_f32_e32 v197, v225, v197
	s_nop 1
	s_waitcnt lgkmcnt(1)
	v_mfma_f32_16x16x32_bf16 v[100:103], v[148:151], v[156:159], v[194:197]
	s_waitcnt lgkmcnt(0)
	v_mfma_f32_16x16x32_bf16 v[104:107], v[152:155], v[160:163], v[194:197]
	s_nop 2
	v_add_f32_e32 v194, v225, v194
	v_add_f32_e32 v195, v225, v195
	v_add_f32_e32 v196, v225, v196
	v_add_f32_e32 v197, v225, v197
	v_mfma_f32_16x16x32_bf16 v[52:55], v[228:231], v[116:119], v[52:55]
	v_exp_f32_e32 v92, v92
	v_exp_f32_e32 v93, v93
	v_mfma_f32_16x16x32_bf16 v[48:51], v[228:231], v[120:123], v[48:51]
	v_exp_f32_e32 v94, v94
	v_exp_f32_e32 v95, v95
	v_mfma_f32_16x16x32_bf16 v[44:47], v[124:127], v[116:119], v[44:47]
	v_exp_f32_e32 v100, v100
	v_exp_f32_e32 v101, v101
	v_mfma_f32_16x16x32_bf16 v[32:35], v[124:127], v[120:123], v[32:35]
	v_exp_f32_e32 v102, v102
	v_exp_f32_e32 v103, v103
	v_mfma_f32_16x16x32_bf16 v[40:43], v[128:131], v[116:119], v[40:43]
	v_cvt_pk_bf16_f32 v108, v92, v93
	v_cvt_pk_bf16_f32 v109, v94, v95
	v_cvt_pk_bf16_f32 v110, v100, v101
	v_mfma_f32_16x16x32_bf16 v[24:27], v[128:131], v[120:123], v[24:27]
	v_cvt_pk_bf16_f32 v111, v102, v103
	v_exp_f32_e32 v96, v96
	v_exp_f32_e32 v97, v97
	v_mfma_f32_16x16x32_bf16 v[36:39], v[132:135], v[116:119], v[36:39]
	v_exp_f32_e32 v98, v98
	v_exp_f32_e32 v99, v99
	v_mfma_f32_16x16x32_bf16 v[20:23], v[132:135], v[120:123], v[20:23]
	v_exp_f32_e32 v104, v104
	v_exp_f32_e32 v105, v105
	v_mfma_f32_16x16x32_bf16 v[28:31], v[136:139], v[116:119], v[28:31]
	v_exp_f32_e32 v106, v106
	v_exp_f32_e32 v107, v107
	v_mfma_f32_16x16x32_bf16 v[16:19], v[136:139], v[120:123], v[16:19]
	v_cvt_pk_bf16_f32 v112, v96, v97
	v_cvt_pk_bf16_f32 v113, v98, v99
	v_cvt_pk_bf16_f32 v114, v104, v105
	v_cvt_pk_bf16_f32 v115, v106, v107
	v_mfma_f32_16x16x32_bf16 v[92:95], v[140:143], v[242:245], v[220:223]
	v_mfma_f32_16x16x32_bf16 v[96:99], v[144:147], v[246:249], v[220:223]
	s_nop 2
	v_add_f32_e32 v220, v225, v220
	v_add_f32_e32 v221, v225, v221
	v_add_f32_e32 v222, v225, v222
	v_add_f32_e32 v223, v225, v223
	s_nop 1
	v_mfma_f32_16x16x32_bf16 v[100:103], v[148:151], v[242:245], v[220:223]
	v_mfma_f32_16x16x32_bf16 v[104:107], v[152:155], v[246:249], v[220:223]
	s_cmpk_eq_i32 s46, 0x780
	s_cbranch_scc1 .Lb2_skip2_f
	v_add_u32_e32 v219, s1, v182
	s_waitcnt vmcnt(1)
	ds_write_b128 v219, v[4:7]
	s_waitcnt vmcnt(0)
	ds_write_b128 v219, v[8:11] offset:36864
	v_add_co_u32_e32 v4, vcc, 0xff800000, v180
	s_nop 1
	v_addc_co_u32_e32 v5, vcc, -1, v181, vcc
	global_load_dwordx4 v[4:7], v[4:5], off
	s_nop 0
	global_load_dwordx4 v[8:11], v[180:181], off
.Lb2_skip2_f:
	ds_read_b64_tr_b16 v[124:125], v217 offset:46080
	ds_read_b64_tr_b16 v[126:127], v217 offset:48384
	ds_read_b64_tr_b16 v[128:129], v217 offset:46112
	ds_read_b64_tr_b16 v[130:131], v217 offset:48416
	ds_read_b64_tr_b16 v[132:133], v217 offset:46144
	ds_read_b64_tr_b16 v[134:135], v217 offset:48448
	ds_read_b64_tr_b16 v[136:137], v217 offset:46176
	ds_read_b64_tr_b16 v[138:139], v217 offset:48480
	s_nop 2
	v_add_f32_e32 v220, v225, v220
	v_add_f32_e32 v221, v225, v221
	v_add_f32_e32 v222, v225, v222
	v_add_f32_e32 v223, v225, v223
	ds_read_b128 v[140:143], v218 offset:13824
	ds_read_b128 v[144:147], v218 offset:13888
	ds_read_b128 v[148:151], v218 offset:16128
	ds_read_b128 v[152:155], v218 offset:16192
	v_mfma_f32_16x16x32_bf16 v[88:91], v[228:231], v[108:111], v[88:91]
	v_exp_f32_e32 v92, v92
	v_exp_f32_e32 v93, v93
	v_mfma_f32_16x16x32_bf16 v[84:87], v[228:231], v[112:115], v[84:87]
	v_exp_f32_e32 v94, v94
	v_exp_f32_e32 v95, v95
	s_waitcnt lgkmcnt(10)
	v_mfma_f32_16x16x32_bf16 v[80:83], v[124:127], v[108:111], v[80:83]
	v_exp_f32_e32 v100, v100
	v_exp_f32_e32 v101, v101
	v_mfma_f32_16x16x32_bf16 v[12:15], v[124:127], v[112:115], v[12:15]
	v_exp_f32_e32 v102, v102
	v_exp_f32_e32 v103, v103
	s_waitcnt lgkmcnt(8)
	v_mfma_f32_16x16x32_bf16 v[76:79], v[128:131], v[108:111], v[76:79]
	v_cvt_pk_bf16_f32 v116, v92, v93
	v_cvt_pk_bf16_f32 v117, v94, v95
	v_cvt_pk_bf16_f32 v118, v100, v101
	v_mfma_f32_16x16x32_bf16 v[64:67], v[128:131], v[112:115], v[64:67]
	v_cvt_pk_bf16_f32 v119, v102, v103
	v_exp_f32_e32 v96, v96
	v_exp_f32_e32 v97, v97
	s_waitcnt lgkmcnt(6)
; #define LAS __attribute__((address_space(3)))
; DI void mixerB2_unit(int u, int l, const bf16* PROJ, bf16* YC, const float* dlam_l, const float* dnw_l, const float* kmax_l, LAS char* lds, int tid, int wave, int lane) {
;     ...
;         SBlk SA, SB;
;         B_QK(SA, 0, 0); B_QK(SB, 0, 1);
;         B_SMPV(SA, 0, 0);
;         if (kt128 + 1 < 16) { const size_t ro = (size_t)(128 * (kt128 + 1) + lrow) * 64 + lch * 8; rk = *(const u32x4*)(kbase + ro); rv = *(const u32x4*)(vbase + ro); }
;         B_QK(SA, 1, 0);
;         B_SMPV(SB, 0, 1);
;         B_QK(SB, 1, 1);
;         if (kt128 + 1 < 16) { LAS char* Kn = Kb + ((kt128 + 1) & 1) * KV_TILE; LAS char* Vn = Vb + ((kt128 + 1) & 1) * KV_TILE;
;             *(LAS u32x4*)(Kn + lrow * KV_PITCH + lch * 16) = rk; *(LAS u32x4*)(Vn + lrow * KV_PITCH + lch * 16) = rv;
;             const size_t ro = (size_t)(128 * (kt128 + 1) + 64 + lrow) * 64 + lch * 8; rk = *(const u32x4*)(kbase + ro); rv = *(const u32x4*)(vbase + ro); }
;         B_SMPV(SA, 1, 0);
;         B_SMPV(SB, 1, 1);
;     ...
;         }
;         if (kt128 + 1 < 16) { LAS char* Kn = Kb + ((kt128 + 1) & 1) * KV_TILE; LAS char* Vn = Vb + ((kt128 + 1) & 1) * KV_TILE;
;             *(LAS u32x4*)(Kn + (lrow + 64) * KV_PITCH + lch * 16) = rk; *(LAS u32x4*)(Vn + (lrow + 64) * KV_PITCH + lch * 16) = rv; }
;         __syncthreads();
;     }
	v_mfma_f32_16x16x32_bf16 v[72:75], v[132:135], v[108:111], v[72:75]
	v_exp_f32_e32 v98, v98
	v_exp_f32_e32 v99, v99
	v_mfma_f32_16x16x32_bf16 v[60:63], v[132:135], v[112:115], v[60:63]
	v_exp_f32_e32 v104, v104
	v_exp_f32_e32 v105, v105
	s_waitcnt lgkmcnt(4)
	v_mfma_f32_16x16x32_bf16 v[68:71], v[136:139], v[108:111], v[68:71]
	v_exp_f32_e32 v106, v106
	v_exp_f32_e32 v107, v107
	v_mfma_f32_16x16x32_bf16 v[56:59], v[136:139], v[112:115], v[56:59]
	v_cvt_pk_bf16_f32 v120, v96, v97
	v_cvt_pk_bf16_f32 v121, v98, v99
	v_cvt_pk_bf16_f32 v122, v104, v105
	v_cvt_pk_bf16_f32 v123, v106, v107
	s_waitcnt lgkmcnt(3)
	v_mfma_f32_16x16x32_bf16 v[92:95], v[140:143], v[156:159], v[194:197]
	s_waitcnt lgkmcnt(2)
	v_mfma_f32_16x16x32_bf16 v[96:99], v[144:147], v[160:163], v[194:197]
	s_nop 2
	v_add_f32_e32 v194, v225, v194
	v_add_f32_e32 v195, v225, v195
	v_add_f32_e32 v196, v225, v196
	v_add_f32_e32 v197, v225, v197
	s_nop 1
	s_waitcnt lgkmcnt(1)
	v_mfma_f32_16x16x32_bf16 v[100:103], v[148:151], v[156:159], v[194:197]
	s_waitcnt lgkmcnt(0)
	v_mfma_f32_16x16x32_bf16 v[104:107], v[152:155], v[160:163], v[194:197]
	v_mfma_f32_16x16x32_bf16 v[52:55], v[228:231], v[116:119], v[52:55]
	v_exp_f32_e32 v92, v92
	v_exp_f32_e32 v93, v93
	v_mfma_f32_16x16x32_bf16 v[48:51], v[228:231], v[120:123], v[48:51]
	v_exp_f32_e32 v94, v94
	v_exp_f32_e32 v95, v95
	v_mfma_f32_16x16x32_bf16 v[44:47], v[124:127], v[116:119], v[44:47]
	v_exp_f32_e32 v100, v100
	v_exp_f32_e32 v101, v101
	v_mfma_f32_16x16x32_bf16 v[32:35], v[124:127], v[120:123], v[32:35]
	v_exp_f32_e32 v102, v102
	v_exp_f32_e32 v103, v103
	v_mfma_f32_16x16x32_bf16 v[40:43], v[128:131], v[116:119], v[40:43]
	v_cvt_pk_bf16_f32 v108, v92, v93
	v_cvt_pk_bf16_f32 v109, v94, v95
	v_cvt_pk_bf16_f32 v110, v100, v101
	v_mfma_f32_16x16x32_bf16 v[24:27], v[128:131], v[120:123], v[24:27]
	v_cvt_pk_bf16_f32 v111, v102, v103
	v_exp_f32_e32 v96, v96
	v_exp_f32_e32 v97, v97
	v_mfma_f32_16x16x32_bf16 v[36:39], v[132:135], v[116:119], v[36:39]
	v_exp_f32_e32 v98, v98
	v_exp_f32_e32 v99, v99
	v_mfma_f32_16x16x32_bf16 v[20:23], v[132:135], v[120:123], v[20:23]
	v_exp_f32_e32 v104, v104
	v_exp_f32_e32 v105, v105
	v_mfma_f32_16x16x32_bf16 v[28:31], v[136:139], v[116:119], v[28:31]
	v_exp_f32_e32 v106, v106
	v_exp_f32_e32 v107, v107
	v_mfma_f32_16x16x32_bf16 v[16:19], v[136:139], v[120:123], v[16:19]
	v_cvt_pk_bf16_f32 v112, v96, v97
	v_cvt_pk_bf16_f32 v113, v98, v99
	v_cvt_pk_bf16_f32 v114, v104, v105
	v_cvt_pk_bf16_f32 v115, v106, v107
	v_mfma_f32_16x16x32_bf16 v[92:95], v[140:143], v[242:245], v[220:223]
	v_mfma_f32_16x16x32_bf16 v[96:99], v[144:147], v[246:249], v[220:223]
	s_nop 2
	v_add_f32_e32 v220, v225, v220
	v_add_f32_e32 v221, v225, v221
	v_add_f32_e32 v222, v225, v222
	v_add_f32_e32 v223, v225, v223
	s_nop 1
	v_mfma_f32_16x16x32_bf16 v[100:103], v[148:151], v[242:245], v[220:223]
	v_mfma_f32_16x16x32_bf16 v[104:107], v[152:155], v[246:249], v[220:223]
	ds_read_b64_tr_b16 v[124:125], v217 offset:50688
	ds_read_b64_tr_b16 v[126:127], v217 offset:52992
	ds_read_b64_tr_b16 v[128:129], v217 offset:50720
	ds_read_b64_tr_b16 v[130:131], v217 offset:53024
	ds_read_b64_tr_b16 v[132:133], v217 offset:50752
	ds_read_b64_tr_b16 v[134:135], v217 offset:53056
	ds_read_b64_tr_b16 v[136:137], v217 offset:50784
	ds_read_b64_tr_b16 v[138:139], v217 offset:53088
	v_mfma_f32_16x16x32_bf16 v[88:91], v[228:231], v[108:111], v[88:91]
	v_exp_f32_e32 v92, v92
	v_exp_f32_e32 v93, v93
	v_mfma_f32_16x16x32_bf16 v[84:87], v[228:231], v[112:115], v[84:87]
	v_exp_f32_e32 v94, v94
	v_exp_f32_e32 v95, v95
	s_waitcnt lgkmcnt(6)
	v_mfma_f32_16x16x32_bf16 v[80:83], v[124:127], v[108:111], v[80:83]
	v_exp_f32_e32 v100, v100
	v_exp_f32_e32 v101, v101
	v_mfma_f32_16x16x32_bf16 v[12:15], v[124:127], v[112:115], v[12:15]
	v_exp_f32_e32 v102, v102
	v_exp_f32_e32 v103, v103
	s_waitcnt lgkmcnt(4)
	v_mfma_f32_16x16x32_bf16 v[76:79], v[128:131], v[108:111], v[76:79]
	v_cvt_pk_bf16_f32 v116, v92, v93
	v_cvt_pk_bf16_f32 v117, v94, v95
	v_cvt_pk_bf16_f32 v118, v100, v101
	s_cmpk_eq_i32 s46, 0x780
	s_cbranch_scc1 .Lb2_skip3_f
	v_add_u32_e32 v219, s1, v183
	s_waitcnt vmcnt(1)
	ds_write_b128 v219, v[4:7]
	s_waitcnt vmcnt(0)
	ds_write_b128 v219, v[8:11] offset:36864
	v_add_co_u32_e32 v180, vcc, 0x4000, v180
	s_nop 1
	v_addc_co_u32_e32 v181, vcc, 0, v181, vcc
.Lb2_skip3_f:
	s_waitcnt lgkmcnt(0)
	s_barrier
	s_xor_b32 s0, s0, 0x4800
	s_xor_b32 s1, s1, 0x4800
	s_addk_i32 s46, 0x80
	s_add_i32 s45, s45, 1
	v_add_u32_e32 v218, s0, v232
	v_add_u32_e32 v217, s0, v250
	s_add_i32 s40, s44, s46
	ds_read_b128 v[140:143], v218
	ds_read_b128 v[144:147], v218 offset:64
	ds_read_b128 v[148:151], v218 offset:2304
	ds_read_b128 v[152:155], v218 offset:2368
	v_mfma_f32_16x16x32_bf16 v[64:67], v[128:131], v[112:115], v[64:67]
	v_cvt_pk_bf16_f32 v119, v102, v103
	v_exp_f32_e32 v96, v96
	v_exp_f32_e32 v97, v97
	v_mfma_f32_16x16x32_bf16 v[72:75], v[132:135], v[108:111], v[72:75]
	v_exp_f32_e32 v98, v98
	v_exp_f32_e32 v99, v99
	v_mfma_f32_16x16x32_bf16 v[60:63], v[132:135], v[112:115], v[60:63]
	v_exp_f32_e32 v104, v104
	v_exp_f32_e32 v105, v105
	v_mfma_f32_16x16x32_bf16 v[68:71], v[136:139], v[108:111], v[68:71]
	v_exp_f32_e32 v106, v106
	v_exp_f32_e32 v107, v107
	v_mfma_f32_16x16x32_bf16 v[56:59], v[136:139], v[112:115], v[56:59]
	v_cvt_pk_bf16_f32 v120, v96, v97
	v_cvt_pk_bf16_f32 v121, v98, v99
	v_cvt_pk_bf16_f32 v122, v104, v105
	v_cvt_pk_bf16_f32 v123, v106, v107
	s_cmpk_eq_i32 s46, 0x800
	s_cbranch_scc1 .Lb2_drain
	s_branch .Lb2_top
; #define LAS __attribute__((address_space(3)))
; DI float alibi_c(float dkf, float pf, float nslope2, float nbound) { float t, c;
;     asm("v_add_f32_e32 %0, %1, %2" : "=v"(t) : "s"(dkf), "v"(pf));
;     asm("v_fma_f32 %0, |%1|, %2, %3" : "=v"(c) : "v"(t), "s"(nslope2), "v"(nbound));
;     return c; }
; DI void mixerB2_unit(int u, int l, const bf16* PROJ, bf16* YC, const float* dlam_l, const float* dnw_l, const float* kmax_l, LAS char* lds, int tid, int wave, int lane) {
;     ...
;     for (int kt128 = 0; kt128 < 16; ++kt128) {
;         {
;         const LAS char* K0 = Kb + (kt128 & 1) * KV_TILE; const LAS char* V0 = Vb + (kt128 & 1) * KV_TILE;
;     ...
;         SBlk SA, SB;
;         B_QK(SA, 0, 0); B_QK(SB, 0, 1);
;         B_SMPV(SA, 0, 0);
;         if (kt128 + 1 < 16) { const size_t ro = (size_t)(128 * (kt128 + 1) + lrow) * 64 + lch * 8; rk = *(const u32x4*)(kbase + ro); rv = *(const u32x4*)(vbase + ro); }
;         B_QK(SA, 1, 0);
;         B_SMPV(SB, 0, 1);
.Lb2_near:
	s_add_i32 s41, s40, 0
	v_cvt_f32_i32_e32 v219, s41
	v_add_f32_e32 v194, v219, v186
	v_add_f32_e32 v195, v219, v187
	v_add_f32_e32 v196, v219, v191
	v_add_f32_e32 v197, v219, v193
	v_add_f32_e32 v220, 0x41800000, v194
	v_add_f32_e32 v221, 0x41800000, v195
	v_add_f32_e32 v222, 0x41800000, v196
	v_add_f32_e32 v223, 0x41800000, v197
	v_fma_f32 v194, |v194|, v214, v215
	v_fma_f32 v195, |v195|, v214, v215
	v_fma_f32 v196, |v196|, v214, v215
	v_fma_f32 v197, |v197|, v214, v215
	v_fma_f32 v220, |v220|, v214, v215
	v_fma_f32 v221, |v221|, v214, v215
	v_fma_f32 v222, |v222|, v214, v215
	v_fma_f32 v223, |v223|, v214, v215
	s_waitcnt lgkmcnt(3)
	v_mfma_f32_16x16x32_bf16 v[92:95], v[140:143], v[156:159], v[194:197]
	s_waitcnt lgkmcnt(2)
	v_mfma_f32_16x16x32_bf16 v[96:99], v[144:147], v[160:163], v[194:197]
	s_waitcnt lgkmcnt(1)
	v_mfma_f32_16x16x32_bf16 v[100:103], v[148:151], v[156:159], v[220:223]
	s_waitcnt lgkmcnt(0)
	v_mfma_f32_16x16x32_bf16 v[104:107], v[152:155], v[160:163], v[220:223]
	s_nop 3
	v_mfma_f32_16x16x32_bf16 v[52:55], v[228:231], v[116:119], v[52:55]
	v_exp_f32_e32 v92, v92
	v_exp_f32_e32 v93, v93
	v_mfma_f32_16x16x32_bf16 v[48:51], v[228:231], v[120:123], v[48:51]
	v_exp_f32_e32 v94, v94
	v_exp_f32_e32 v95, v95
	v_mfma_f32_16x16x32_bf16 v[44:47], v[124:127], v[116:119], v[44:47]
	v_exp_f32_e32 v100, v100
	v_exp_f32_e32 v101, v101
	v_mfma_f32_16x16x32_bf16 v[32:35], v[124:127], v[120:123], v[32:35]
	v_exp_f32_e32 v102, v102
	v_exp_f32_e32 v103, v103
	v_mfma_f32_16x16x32_bf16 v[40:43], v[128:131], v[116:119], v[40:43]
	v_cvt_pk_bf16_f32 v108, v92, v93
	v_cvt_pk_bf16_f32 v109, v94, v95
	v_cvt_pk_bf16_f32 v110, v100, v101
	v_mfma_f32_16x16x32_bf16 v[24:27], v[128:131], v[120:123], v[24:27]
	v_cvt_pk_bf16_f32 v111, v102, v103
	v_exp_f32_e32 v96, v96
	v_exp_f32_e32 v97, v97
	v_mfma_f32_16x16x32_bf16 v[36:39], v[132:135], v[116:119], v[36:39]
	v_exp_f32_e32 v98, v98
	v_exp_f32_e32 v99, v99
	v_mfma_f32_16x16x32_bf16 v[20:23], v[132:135], v[120:123], v[20:23]
	v_exp_f32_e32 v104, v104
	v_exp_f32_e32 v105, v105
	v_mfma_f32_16x16x32_bf16 v[28:31], v[136:139], v[116:119], v[28:31]
	v_exp_f32_e32 v106, v106
	v_exp_f32_e32 v107, v107
	v_mfma_f32_16x16x32_bf16 v[16:19], v[136:139], v[120:123], v[16:19]
	v_cvt_pk_bf16_f32 v112, v96, v97
	v_cvt_pk_bf16_f32 v113, v98, v99
	v_cvt_pk_bf16_f32 v114, v104, v105
	v_cvt_pk_bf16_f32 v115, v106, v107
	s_sub_i32 s41, s40, 16
	v_cvt_f32_i32_e32 v219, s41
	v_add_f32_e32 v194, v219, v186
	v_add_f32_e32 v195, v219, v187
	v_add_f32_e32 v196, v219, v191
	v_add_f32_e32 v197, v219, v193
	v_add_f32_e32 v220, 0x41800000, v194
	v_add_f32_e32 v221, 0x41800000, v195
	v_add_f32_e32 v222, 0x41800000, v196
	v_add_f32_e32 v223, 0x41800000, v197
	v_fma_f32 v194, |v194|, v214, v216
	v_fma_f32 v195, |v195|, v214, v216
	v_fma_f32 v196, |v196|, v214, v216
	v_fma_f32 v197, |v197|, v214, v216
	v_fma_f32 v220, |v220|, v214, v216
	v_fma_f32 v221, |v221|, v214, v216
	v_fma_f32 v222, |v222|, v214, v216
	v_fma_f32 v223, |v223|, v214, v216
	v_mfma_f32_16x16x32_bf16 v[92:95], v[140:143], v[242:245], v[194:197]
	v_mfma_f32_16x16x32_bf16 v[96:99], v[144:147], v[246:249], v[194:197]
	v_mfma_f32_16x16x32_bf16 v[100:103], v[148:151], v[242:245], v[220:223]
	v_mfma_f32_16x16x32_bf16 v[104:107], v[152:155], v[246:249], v[220:223]
	s_nop 3
	s_cmpk_eq_i32 s46, 0x780
	s_cbranch_scc1 .Lb2_skip1_n
	v_add_co_u32_e32 v4, vcc, 0xff7fe000, v180
	s_nop 1
	v_addc_co_u32_e32 v5, vcc, -1, v181, vcc
	v_add_co_u32_e32 v8, vcc, 0xffffe000, v180
	s_nop 1
	v_addc_co_u32_e32 v9, vcc, -1, v181, vcc
	global_load_dwordx4 v[4:7], v[4:5], off
	s_nop 0
	global_load_dwordx4 v[8:11], v[8:9], off
.Lb2_skip1_n:
	ds_read_b64_tr_b16 v[124:125], v217 offset:36864
	ds_read_b64_tr_b16 v[126:127], v217 offset:39168
	ds_read_b64_tr_b16 v[128:129], v217 offset:36896
	ds_read_b64_tr_b16 v[130:131], v217 offset:39200
	ds_read_b64_tr_b16 v[132:133], v217 offset:36928
	ds_read_b64_tr_b16 v[134:135], v217 offset:39232
	ds_read_b64_tr_b16 v[136:137], v217 offset:36960
	ds_read_b64_tr_b16 v[138:139], v217 offset:39264
	ds_read_b128 v[140:143], v218 offset:4608
	ds_read_b128 v[144:147], v218 offset:4672
	ds_read_b128 v[148:151], v218 offset:6912
	ds_read_b128 v[152:155], v218 offset:6976
	v_mfma_f32_16x16x32_bf16 v[88:91], v[228:231], v[108:111], v[88:91]
	v_exp_f32_e32 v92, v92
	v_exp_f32_e32 v93, v93
	v_mfma_f32_16x16x32_bf16 v[84:87], v[228:231], v[112:115], v[84:87]
	v_exp_f32_e32 v94, v94
	v_exp_f32_e32 v95, v95
	s_waitcnt lgkmcnt(10)
	v_mfma_f32_16x16x32_bf16 v[80:83], v[124:127], v[108:111], v[80:83]
	v_exp_f32_e32 v100, v100
	v_exp_f32_e32 v101, v101
	v_mfma_f32_16x16x32_bf16 v[12:15], v[124:127], v[112:115], v[12:15]
	v_exp_f32_e32 v102, v102
	v_exp_f32_e32 v103, v103
	s_waitcnt lgkmcnt(8)
	v_mfma_f32_16x16x32_bf16 v[76:79], v[128:131], v[108:111], v[76:79]
	v_cvt_pk_bf16_f32 v116, v92, v93
	v_cvt_pk_bf16_f32 v117, v94, v95
	v_cvt_pk_bf16_f32 v118, v100, v101
	v_mfma_f32_16x16x32_bf16 v[64:67], v[128:131], v[112:115], v[64:67]
	v_cvt_pk_bf16_f32 v119, v102, v103
	v_exp_f32_e32 v96, v96
	v_exp_f32_e32 v97, v97
	s_waitcnt lgkmcnt(6)
	v_mfma_f32_16x16x32_bf16 v[72:75], v[132:135], v[108:111], v[72:75]
	v_exp_f32_e32 v98, v98
	v_exp_f32_e32 v99, v99
	v_mfma_f32_16x16x32_bf16 v[60:63], v[132:135], v[112:115], v[60:63]
	v_exp_f32_e32 v104, v104
	v_exp_f32_e32 v105, v105
	s_waitcnt lgkmcnt(4)
; DI float alibi_c(float dkf, float pf, float nslope2, float nbound) { float t, c;
;     asm("v_add_f32_e32 %0, %1, %2" : "=v"(t) : "s"(dkf), "v"(pf));
;     asm("v_fma_f32 %0, |%1|, %2, %3" : "=v"(c) : "v"(t), "s"(nslope2), "v"(nbound));
;     return c; }
; DI void mixerB2_unit(int u, int l, const bf16* PROJ, bf16* YC, const float* dlam_l, const float* dnw_l, const float* kmax_l, LAS char* lds, int tid, int wave, int lane) {
;     ...
;         SBlk SA, SB;
;         B_QK(SA, 0, 0); B_QK(SB, 0, 1);
;         B_SMPV(SA, 0, 0);
;         if (kt128 + 1 < 16) { const size_t ro = (size_t)(128 * (kt128 + 1) + lrow) * 64 + lch * 8; rk = *(const u32x4*)(kbase + ro); rv = *(const u32x4*)(vbase + ro); }
;         B_QK(SA, 1, 0);
;         B_SMPV(SB, 0, 1);
	v_mfma_f32_16x16x32_bf16 v[68:71], v[136:139], v[108:111], v[68:71]
	v_exp_f32_e32 v106, v106
	v_exp_f32_e32 v107, v107
	v_mfma_f32_16x16x32_bf16 v[56:59], v[136:139], v[112:115], v[56:59]
	v_cvt_pk_bf16_f32 v120, v96, v97
	v_cvt_pk_bf16_f32 v121, v98, v99
	v_cvt_pk_bf16_f32 v122, v104, v105
	v_cvt_pk_bf16_f32 v123, v106, v107
	s_add_i32 s41, s40, 32
	v_cvt_f32_i32_e32 v219, s41
	v_add_f32_e32 v194, v219, v186
	v_add_f32_e32 v195, v219, v187
	v_add_f32_e32 v196, v219, v191
	v_add_f32_e32 v197, v219, v193
	v_add_f32_e32 v220, 0x41800000, v194
	v_add_f32_e32 v221, 0x41800000, v195
	v_add_f32_e32 v222, 0x41800000, v196
	v_add_f32_e32 v223, 0x41800000, v197
	v_fma_f32 v194, |v194|, v214, v215
	v_fma_f32 v195, |v195|, v214, v215
	v_fma_f32 v196, |v196|, v214, v215
	v_fma_f32 v197, |v197|, v214, v215
	v_fma_f32 v220, |v220|, v214, v215
	v_fma_f32 v221, |v221|, v214, v215
	v_fma_f32 v222, |v222|, v214, v215
	v_fma_f32 v223, |v223|, v214, v215
	s_waitcnt lgkmcnt(3)
	v_mfma_f32_16x16x32_bf16 v[92:95], v[140:143], v[156:159], v[194:197]
	s_waitcnt lgkmcnt(2)
	v_mfma_f32_16x16x32_bf16 v[96:99], v[144:147], v[160:163], v[194:197]
	s_waitcnt lgkmcnt(1)
	v_mfma_f32_16x16x32_bf16 v[100:103], v[148:151], v[156:159], v[220:223]
	s_waitcnt lgkmcnt(0)
	v_mfma_f32_16x16x32_bf16 v[104:107], v[152:155], v[160:163], v[220:223]
	s_nop 3
	v_mfma_f32_16x16x32_bf16 v[52:55], v[228:231], v[116:119], v[52:55]
	v_exp_f32_e32 v92, v92
	v_exp_f32_e32 v93, v93
	v_mfma_f32_16x16x32_bf16 v[48:51], v[228:231], v[120:123], v[48:51]
	v_exp_f32_e32 v94, v94
	v_exp_f32_e32 v95, v95
	v_mfma_f32_16x16x32_bf16 v[44:47], v[124:127], v[116:119], v[44:47]
	v_exp_f32_e32 v100, v100
	v_exp_f32_e32 v101, v101
	v_mfma_f32_16x16x32_bf16 v[32:35], v[124:127], v[120:123], v[32:35]
	v_exp_f32_e32 v102, v102
	v_exp_f32_e32 v103, v103
	v_mfma_f32_16x16x32_bf16 v[40:43], v[128:131], v[116:119], v[40:43]
	v_cvt_pk_bf16_f32 v108, v92, v93
	v_cvt_pk_bf16_f32 v109, v94, v95
	v_cvt_pk_bf16_f32 v110, v100, v101
	v_mfma_f32_16x16x32_bf16 v[24:27], v[128:131], v[120:123], v[24:27]
	v_cvt_pk_bf16_f32 v111, v102, v103
	v_exp_f32_e32 v96, v96
	v_exp_f32_e32 v97, v97
	v_mfma_f32_16x16x32_bf16 v[36:39], v[132:135], v[116:119], v[36:39]
	v_exp_f32_e32 v98, v98
	v_exp_f32_e32 v99, v99
	v_mfma_f32_16x16x32_bf16 v[20:23], v[132:135], v[120:123], v[20:23]
	v_exp_f32_e32 v104, v104
	v_exp_f32_e32 v105, v105
	v_mfma_f32_16x16x32_bf16 v[28:31], v[136:139], v[116:119], v[28:31]
	v_exp_f32_e32 v106, v106
	v_exp_f32_e32 v107, v107
	v_mfma_f32_16x16x32_bf16 v[16:19], v[136:139], v[120:123], v[16:19]
	v_cvt_pk_bf16_f32 v112, v96, v97
	v_cvt_pk_bf16_f32 v113, v98, v99
	v_cvt_pk_bf16_f32 v114, v104, v105
	v_cvt_pk_bf16_f32 v115, v106, v107
	s_add_i32 s41, s40, 16
	v_cvt_f32_i32_e32 v219, s41
	v_add_f32_e32 v194, v219, v186
	v_add_f32_e32 v195, v219, v187
	v_add_f32_e32 v196, v219, v191
	v_add_f32_e32 v197, v219, v193
	v_add_f32_e32 v220, 0x41800000, v194
	v_add_f32_e32 v221, 0x41800000, v195
	v_add_f32_e32 v222, 0x41800000, v196
	v_add_f32_e32 v223, 0x41800000, v197
	v_fma_f32 v194, |v194|, v214, v216
	v_fma_f32 v195, |v195|, v214, v216
	v_fma_f32 v196, |v196|, v214, v216
	v_fma_f32 v197, |v197|, v214, v216
	v_fma_f32 v220, |v220|, v214, v216
	v_fma_f32 v221, |v221|, v214, v216
	v_fma_f32 v222, |v222|, v214, v216
	v_fma_f32 v223, |v223|, v214, v216
	v_mfma_f32_16x16x32_bf16 v[92:95], v[140:143], v[242:245], v[194:197]
	v_mfma_f32_16x16x32_bf16 v[96:99], v[144:147], v[246:249], v[194:197]
	v_mfma_f32_16x16x32_bf16 v[100:103], v[148:151], v[242:245], v[220:223]
	v_mfma_f32_16x16x32_bf16 v[104:107], v[152:155], v[246:249], v[220:223]
	s_nop 3
	ds_read_b64_tr_b16 v[124:125], v217 offset:41472
	ds_read_b64_tr_b16 v[126:127], v217 offset:43776
	ds_read_b64_tr_b16 v[128:129], v217 offset:41504
	ds_read_b64_tr_b16 v[130:131], v217 offset:43808
	ds_read_b64_tr_b16 v[132:133], v217 offset:41536
	ds_read_b64_tr_b16 v[134:135], v217 offset:43840
	ds_read_b64_tr_b16 v[136:137], v217 offset:41568
	ds_read_b64_tr_b16 v[138:139], v217 offset:43872
	ds_read_b128 v[140:143], v218 offset:9216
	ds_read_b128 v[144:147], v218 offset:9280
	ds_read_b128 v[148:151], v218 offset:11520
	ds_read_b128 v[152:155], v218 offset:11584
	v_mfma_f32_16x16x32_bf16 v[88:91], v[228:231], v[108:111], v[88:91]
	v_exp_f32_e32 v92, v92
	v_exp_f32_e32 v93, v93
	v_mfma_f32_16x16x32_bf16 v[84:87], v[228:231], v[112:115], v[84:87]
	v_exp_f32_e32 v94, v94
	v_exp_f32_e32 v95, v95
	s_waitcnt lgkmcnt(10)
	v_mfma_f32_16x16x32_bf16 v[80:83], v[124:127], v[108:111], v[80:83]
	v_exp_f32_e32 v100, v100
	v_exp_f32_e32 v101, v101
	v_mfma_f32_16x16x32_bf16 v[12:15], v[124:127], v[112:115], v[12:15]
	v_exp_f32_e32 v102, v102
	v_exp_f32_e32 v103, v103
	s_waitcnt lgkmcnt(8)
	v_mfma_f32_16x16x32_bf16 v[76:79], v[128:131], v[108:111], v[76:79]
	v_cvt_pk_bf16_f32 v116, v92, v93
	v_cvt_pk_bf16_f32 v117, v94, v95
	v_cvt_pk_bf16_f32 v118, v100, v101
	v_mfma_f32_16x16x32_bf16 v[64:67], v[128:131], v[112:115], v[64:67]
	v_cvt_pk_bf16_f32 v119, v102, v103
	v_exp_f32_e32 v96, v96
	v_exp_f32_e32 v97, v97
	s_waitcnt lgkmcnt(6)
	v_mfma_f32_16x16x32_bf16 v[72:75], v[132:135], v[108:111], v[72:75]
	v_exp_f32_e32 v98, v98
	v_exp_f32_e32 v99, v99
	v_mfma_f32_16x16x32_bf16 v[60:63], v[132:135], v[112:115], v[60:63]
	v_exp_f32_e32 v104, v104
	v_exp_f32_e32 v105, v105
	s_waitcnt lgkmcnt(4)
; #define LAS __attribute__((address_space(3)))
; DI float alibi_c(float dkf, float pf, float nslope2, float nbound) { float t, c;
;     asm("v_add_f32_e32 %0, %1, %2" : "=v"(t) : "s"(dkf), "v"(pf));
;     asm("v_fma_f32 %0, |%1|, %2, %3" : "=v"(c) : "v"(t), "s"(nslope2), "v"(nbound));
;     return c; }
; DI void mixerB2_unit(int u, int l, const bf16* PROJ, bf16* YC, const float* dlam_l, const float* dnw_l, const float* kmax_l, LAS char* lds, int tid, int wave, int lane) {
;     ...
;         SBlk SA, SB;
;         B_QK(SA, 0, 0); B_QK(SB, 0, 1);
;         B_SMPV(SA, 0, 0);
;         if (kt128 + 1 < 16) { const size_t ro = (size_t)(128 * (kt128 + 1) + lrow) * 64 + lch * 8; rk = *(const u32x4*)(kbase + ro); rv = *(const u32x4*)(vbase + ro); }
;         B_QK(SA, 1, 0);
;         B_SMPV(SB, 0, 1);
;         B_QK(SB, 1, 1);
;         if (kt128 + 1 < 16) { LAS char* Kn = Kb + ((kt128 + 1) & 1) * KV_TILE; LAS char* Vn = Vb + ((kt128 + 1) & 1) * KV_TILE;
;             *(LAS u32x4*)(Kn + lrow * KV_PITCH + lch * 16) = rk; *(LAS u32x4*)(Vn + lrow * KV_PITCH + lch * 16) = rv;
;             const size_t ro = (size_t)(128 * (kt128 + 1) + 64 + lrow) * 64 + lch * 8; rk = *(const u32x4*)(kbase + ro); rv = *(const u32x4*)(vbase + ro); }
	v_mfma_f32_16x16x32_bf16 v[68:71], v[136:139], v[108:111], v[68:71]
	v_exp_f32_e32 v106, v106
	v_exp_f32_e32 v107, v107
	v_mfma_f32_16x16x32_bf16 v[56:59], v[136:139], v[112:115], v[56:59]
	v_cvt_pk_bf16_f32 v120, v96, v97
	v_cvt_pk_bf16_f32 v121, v98, v99
	v_cvt_pk_bf16_f32 v122, v104, v105
	v_cvt_pk_bf16_f32 v123, v106, v107
	s_add_i32 s41, s40, 64
	v_cvt_f32_i32_e32 v219, s41
	v_add_f32_e32 v194, v219, v186
	v_add_f32_e32 v195, v219, v187
	v_add_f32_e32 v196, v219, v191
	v_add_f32_e32 v197, v219, v193
	v_add_f32_e32 v220, 0x41800000, v194
	v_add_f32_e32 v221, 0x41800000, v195
	v_add_f32_e32 v222, 0x41800000, v196
	v_add_f32_e32 v223, 0x41800000, v197
	v_fma_f32 v194, |v194|, v214, v215
	v_fma_f32 v195, |v195|, v214, v215
	v_fma_f32 v196, |v196|, v214, v215
	v_fma_f32 v197, |v197|, v214, v215
	v_fma_f32 v220, |v220|, v214, v215
	v_fma_f32 v221, |v221|, v214, v215
	v_fma_f32 v222, |v222|, v214, v215
	v_fma_f32 v223, |v223|, v214, v215
	s_waitcnt lgkmcnt(3)
	v_mfma_f32_16x16x32_bf16 v[92:95], v[140:143], v[156:159], v[194:197]
	s_waitcnt lgkmcnt(2)
	v_mfma_f32_16x16x32_bf16 v[96:99], v[144:147], v[160:163], v[194:197]
	s_waitcnt lgkmcnt(1)
	v_mfma_f32_16x16x32_bf16 v[100:103], v[148:151], v[156:159], v[220:223]
	s_waitcnt lgkmcnt(0)
	v_mfma_f32_16x16x32_bf16 v[104:107], v[152:155], v[160:163], v[220:223]
	s_nop 3
	v_mfma_f32_16x16x32_bf16 v[52:55], v[228:231], v[116:119], v[52:55]
	v_exp_f32_e32 v92, v92
	v_exp_f32_e32 v93, v93
	v_mfma_f32_16x16x32_bf16 v[48:51], v[228:231], v[120:123], v[48:51]
	v_exp_f32_e32 v94, v94
	v_exp_f32_e32 v95, v95
	v_mfma_f32_16x16x32_bf16 v[44:47], v[124:127], v[116:119], v[44:47]
	v_exp_f32_e32 v100, v100
	v_exp_f32_e32 v101, v101
	v_mfma_f32_16x16x32_bf16 v[32:35], v[124:127], v[120:123], v[32:35]
	v_exp_f32_e32 v102, v102
	v_exp_f32_e32 v103, v103
	v_mfma_f32_16x16x32_bf16 v[40:43], v[128:131], v[116:119], v[40:43]
	v_cvt_pk_bf16_f32 v108, v92, v93
	v_cvt_pk_bf16_f32 v109, v94, v95
	v_cvt_pk_bf16_f32 v110, v100, v101
	v_mfma_f32_16x16x32_bf16 v[24:27], v[128:131], v[120:123], v[24:27]
	v_cvt_pk_bf16_f32 v111, v102, v103
	v_exp_f32_e32 v96, v96
	v_exp_f32_e32 v97, v97
	v_mfma_f32_16x16x32_bf16 v[36:39], v[132:135], v[116:119], v[36:39]
	v_exp_f32_e32 v98, v98
	v_exp_f32_e32 v99, v99
	v_mfma_f32_16x16x32_bf16 v[20:23], v[132:135], v[120:123], v[20:23]
	v_exp_f32_e32 v104, v104
	v_exp_f32_e32 v105, v105
	v_mfma_f32_16x16x32_bf16 v[28:31], v[136:139], v[116:119], v[28:31]
	v_exp_f32_e32 v106, v106
	v_exp_f32_e32 v107, v107
	v_mfma_f32_16x16x32_bf16 v[16:19], v[136:139], v[120:123], v[16:19]
	v_cvt_pk_bf16_f32 v112, v96, v97
	v_cvt_pk_bf16_f32 v113, v98, v99
	v_cvt_pk_bf16_f32 v114, v104, v105
	v_cvt_pk_bf16_f32 v115, v106, v107
	s_add_i32 s41, s40, 48
	v_cvt_f32_i32_e32 v219, s41
	v_add_f32_e32 v194, v219, v186
	v_add_f32_e32 v195, v219, v187
	v_add_f32_e32 v196, v219, v191
	v_add_f32_e32 v197, v219, v193
	v_add_f32_e32 v220, 0x41800000, v194
	v_add_f32_e32 v221, 0x41800000, v195
	v_add_f32_e32 v222, 0x41800000, v196
	v_add_f32_e32 v223, 0x41800000, v197
	v_fma_f32 v194, |v194|, v214, v216
	v_fma_f32 v195, |v195|, v214, v216
	v_fma_f32 v196, |v196|, v214, v216
	v_fma_f32 v197, |v197|, v214, v216
	v_fma_f32 v220, |v220|, v214, v216
	v_fma_f32 v221, |v221|, v214, v216
	v_fma_f32 v222, |v222|, v214, v216
	v_fma_f32 v223, |v223|, v214, v216
	v_mfma_f32_16x16x32_bf16 v[92:95], v[140:143], v[242:245], v[194:197]
	v_mfma_f32_16x16x32_bf16 v[96:99], v[144:147], v[246:249], v[194:197]
	v_mfma_f32_16x16x32_bf16 v[100:103], v[148:151], v[242:245], v[220:223]
	v_mfma_f32_16x16x32_bf16 v[104:107], v[152:155], v[246:249], v[220:223]
	s_nop 3
	s_cmpk_eq_i32 s46, 0x780
	s_cbranch_scc1 .Lb2_skip2_n
	v_add_u32_e32 v219, s1, v182
	s_waitcnt vmcnt(1)
	ds_write_b128 v219, v[4:7]
	s_waitcnt vmcnt(0)
	ds_write_b128 v219, v[8:11] offset:36864
	v_add_co_u32_e32 v4, vcc, 0xff800000, v180
	s_nop 1
	v_addc_co_u32_e32 v5, vcc, -1, v181, vcc
	global_load_dwordx4 v[4:7], v[4:5], off
	s_nop 0
	global_load_dwordx4 v[8:11], v[180:181], off
; #define LAS __attribute__((address_space(3)))
; DI float alibi_c(float dkf, float pf, float nslope2, float nbound) { float t, c;
;     asm("v_add_f32_e32 %0, %1, %2" : "=v"(t) : "s"(dkf), "v"(pf));
;     asm("v_fma_f32 %0, |%1|, %2, %3" : "=v"(c) : "v"(t), "s"(nslope2), "v"(nbound));
;     return c; }
; DI void mixerB2_unit(int u, int l, const bf16* PROJ, bf16* YC, const float* dlam_l, const float* dnw_l, const float* kmax_l, LAS char* lds, int tid, int wave, int lane) {
;     ...
;         SBlk SA, SB;
;         B_QK(SA, 0, 0); B_QK(SB, 0, 1);
;         B_SMPV(SA, 0, 0);
;         if (kt128 + 1 < 16) { const size_t ro = (size_t)(128 * (kt128 + 1) + lrow) * 64 + lch * 8; rk = *(const u32x4*)(kbase + ro); rv = *(const u32x4*)(vbase + ro); }
;         B_QK(SA, 1, 0);
;         B_SMPV(SB, 0, 1);
;         B_QK(SB, 1, 1);
;         if (kt128 + 1 < 16) { LAS char* Kn = Kb + ((kt128 + 1) & 1) * KV_TILE; LAS char* Vn = Vb + ((kt128 + 1) & 1) * KV_TILE;
;             *(LAS u32x4*)(Kn + lrow * KV_PITCH + lch * 16) = rk; *(LAS u32x4*)(Vn + lrow * KV_PITCH + lch * 16) = rv;
;             const size_t ro = (size_t)(128 * (kt128 + 1) + 64 + lrow) * 64 + lch * 8; rk = *(const u32x4*)(kbase + ro); rv = *(const u32x4*)(vbase + ro); }
;         B_SMPV(SA, 1, 0);
;         B_SMPV(SB, 1, 1);
;     ...
;         }
;         if (kt128 + 1 < 16) { LAS char* Kn = Kb + ((kt128 + 1) & 1) * KV_TILE; LAS char* Vn = Vb + ((kt128 + 1) & 1) * KV_TILE;
;             *(LAS u32x4*)(Kn + (lrow + 64) * KV_PITCH + lch * 16) = rk; *(LAS u32x4*)(Vn + (lrow + 64) * KV_PITCH + lch * 16) = rv; }
.Lb2_skip2_n:
	ds_read_b64_tr_b16 v[124:125], v217 offset:46080
	ds_read_b64_tr_b16 v[126:127], v217 offset:48384
	ds_read_b64_tr_b16 v[128:129], v217 offset:46112
	ds_read_b64_tr_b16 v[130:131], v217 offset:48416
	ds_read_b64_tr_b16 v[132:133], v217 offset:46144
	ds_read_b64_tr_b16 v[134:135], v217 offset:48448
	ds_read_b64_tr_b16 v[136:137], v217 offset:46176
	ds_read_b64_tr_b16 v[138:139], v217 offset:48480
	ds_read_b128 v[140:143], v218 offset:13824
	ds_read_b128 v[144:147], v218 offset:13888
	ds_read_b128 v[148:151], v218 offset:16128
	ds_read_b128 v[152:155], v218 offset:16192
	v_mfma_f32_16x16x32_bf16 v[88:91], v[228:231], v[108:111], v[88:91]
	v_exp_f32_e32 v92, v92
	v_exp_f32_e32 v93, v93
	v_mfma_f32_16x16x32_bf16 v[84:87], v[228:231], v[112:115], v[84:87]
	v_exp_f32_e32 v94, v94
	v_exp_f32_e32 v95, v95
	s_waitcnt lgkmcnt(10)
	v_mfma_f32_16x16x32_bf16 v[80:83], v[124:127], v[108:111], v[80:83]
	v_exp_f32_e32 v100, v100
	v_exp_f32_e32 v101, v101
	v_mfma_f32_16x16x32_bf16 v[12:15], v[124:127], v[112:115], v[12:15]
	v_exp_f32_e32 v102, v102
	v_exp_f32_e32 v103, v103
	s_waitcnt lgkmcnt(8)
	v_mfma_f32_16x16x32_bf16 v[76:79], v[128:131], v[108:111], v[76:79]
	v_cvt_pk_bf16_f32 v116, v92, v93
	v_cvt_pk_bf16_f32 v117, v94, v95
	v_cvt_pk_bf16_f32 v118, v100, v101
	v_mfma_f32_16x16x32_bf16 v[64:67], v[128:131], v[112:115], v[64:67]
	v_cvt_pk_bf16_f32 v119, v102, v103
	v_exp_f32_e32 v96, v96
	v_exp_f32_e32 v97, v97
	s_waitcnt lgkmcnt(6)
	v_mfma_f32_16x16x32_bf16 v[72:75], v[132:135], v[108:111], v[72:75]
	v_exp_f32_e32 v98, v98
	v_exp_f32_e32 v99, v99
	v_mfma_f32_16x16x32_bf16 v[60:63], v[132:135], v[112:115], v[60:63]
	v_exp_f32_e32 v104, v104
	v_exp_f32_e32 v105, v105
	s_waitcnt lgkmcnt(4)
	v_mfma_f32_16x16x32_bf16 v[68:71], v[136:139], v[108:111], v[68:71]
	v_exp_f32_e32 v106, v106
	v_exp_f32_e32 v107, v107
	v_mfma_f32_16x16x32_bf16 v[56:59], v[136:139], v[112:115], v[56:59]
	v_cvt_pk_bf16_f32 v120, v96, v97
	v_cvt_pk_bf16_f32 v121, v98, v99
	v_cvt_pk_bf16_f32 v122, v104, v105
	v_cvt_pk_bf16_f32 v123, v106, v107
	s_add_i32 s41, s40, 96
	v_cvt_f32_i32_e32 v219, s41
	v_add_f32_e32 v194, v219, v186
	v_add_f32_e32 v195, v219, v187
	v_add_f32_e32 v196, v219, v191
	v_add_f32_e32 v197, v219, v193
	v_add_f32_e32 v220, 0x41800000, v194
	v_add_f32_e32 v221, 0x41800000, v195
	v_add_f32_e32 v222, 0x41800000, v196
	v_add_f32_e32 v223, 0x41800000, v197
	v_fma_f32 v194, |v194|, v214, v215
	v_fma_f32 v195, |v195|, v214, v215
	v_fma_f32 v196, |v196|, v214, v215
	v_fma_f32 v197, |v197|, v214, v215
	v_fma_f32 v220, |v220|, v214, v215
	v_fma_f32 v221, |v221|, v214, v215
	v_fma_f32 v222, |v222|, v214, v215
	v_fma_f32 v223, |v223|, v214, v215
	s_waitcnt lgkmcnt(3)
	v_mfma_f32_16x16x32_bf16 v[92:95], v[140:143], v[156:159], v[194:197]
	s_waitcnt lgkmcnt(2)
	v_mfma_f32_16x16x32_bf16 v[96:99], v[144:147], v[160:163], v[194:197]
	s_waitcnt lgkmcnt(1)
	v_mfma_f32_16x16x32_bf16 v[100:103], v[148:151], v[156:159], v[220:223]
	s_waitcnt lgkmcnt(0)
	v_mfma_f32_16x16x32_bf16 v[104:107], v[152:155], v[160:163], v[220:223]
	s_nop 3
	v_mfma_f32_16x16x32_bf16 v[52:55], v[228:231], v[116:119], v[52:55]
	v_exp_f32_e32 v92, v92
	v_exp_f32_e32 v93, v93
	v_mfma_f32_16x16x32_bf16 v[48:51], v[228:231], v[120:123], v[48:51]
	v_exp_f32_e32 v94, v94
	v_exp_f32_e32 v95, v95
	v_mfma_f32_16x16x32_bf16 v[44:47], v[124:127], v[116:119], v[44:47]
	v_exp_f32_e32 v100, v100
	v_exp_f32_e32 v101, v101
	v_mfma_f32_16x16x32_bf16 v[32:35], v[124:127], v[120:123], v[32:35]
	v_exp_f32_e32 v102, v102
	v_exp_f32_e32 v103, v103
	v_mfma_f32_16x16x32_bf16 v[40:43], v[128:131], v[116:119], v[40:43]
	v_cvt_pk_bf16_f32 v108, v92, v93
	v_cvt_pk_bf16_f32 v109, v94, v95
	v_cvt_pk_bf16_f32 v110, v100, v101
	v_mfma_f32_16x16x32_bf16 v[24:27], v[128:131], v[120:123], v[24:27]
	v_cvt_pk_bf16_f32 v111, v102, v103
	v_exp_f32_e32 v96, v96
	v_exp_f32_e32 v97, v97
	v_mfma_f32_16x16x32_bf16 v[36:39], v[132:135], v[116:119], v[36:39]
	v_exp_f32_e32 v98, v98
	v_exp_f32_e32 v99, v99
	v_mfma_f32_16x16x32_bf16 v[20:23], v[132:135], v[120:123], v[20:23]
	v_exp_f32_e32 v104, v104
	v_exp_f32_e32 v105, v105
	v_mfma_f32_16x16x32_bf16 v[28:31], v[136:139], v[116:119], v[28:31]
	v_exp_f32_e32 v106, v106
	v_exp_f32_e32 v107, v107
	v_mfma_f32_16x16x32_bf16 v[16:19], v[136:139], v[120:123], v[16:19]
	v_cvt_pk_bf16_f32 v112, v96, v97
	v_cvt_pk_bf16_f32 v113, v98, v99
	v_cvt_pk_bf16_f32 v114, v104, v105
	v_cvt_pk_bf16_f32 v115, v106, v107
	s_add_i32 s41, s40, 80
	v_cvt_f32_i32_e32 v219, s41
	v_add_f32_e32 v194, v219, v186
	v_add_f32_e32 v195, v219, v187
	v_add_f32_e32 v196, v219, v191
	v_add_f32_e32 v197, v219, v193
	v_add_f32_e32 v220, 0x41800000, v194
	v_add_f32_e32 v221, 0x41800000, v195
	v_add_f32_e32 v222, 0x41800000, v196
	v_add_f32_e32 v223, 0x41800000, v197
	v_fma_f32 v194, |v194|, v214, v216
	v_fma_f32 v195, |v195|, v214, v216
	v_fma_f32 v196, |v196|, v214, v216
	v_fma_f32 v197, |v197|, v214, v216
	v_fma_f32 v220, |v220|, v214, v216
	v_fma_f32 v221, |v221|, v214, v216
	v_fma_f32 v222, |v222|, v214, v216
	v_fma_f32 v223, |v223|, v214, v216
	v_mfma_f32_16x16x32_bf16 v[92:95], v[140:143], v[242:245], v[194:197]
	v_mfma_f32_16x16x32_bf16 v[96:99], v[144:147], v[246:249], v[194:197]
	v_mfma_f32_16x16x32_bf16 v[100:103], v[148:151], v[242:245], v[220:223]
	v_mfma_f32_16x16x32_bf16 v[104:107], v[152:155], v[246:249], v[220:223]
	s_nop 3
	ds_read_b64_tr_b16 v[124:125], v217 offset:50688
	ds_read_b64_tr_b16 v[126:127], v217 offset:52992
	ds_read_b64_tr_b16 v[128:129], v217 offset:50720
	ds_read_b64_tr_b16 v[130:131], v217 offset:53024
	ds_read_b64_tr_b16 v[132:133], v217 offset:50752
	ds_read_b64_tr_b16 v[134:135], v217 offset:53056
	ds_read_b64_tr_b16 v[136:137], v217 offset:50784
	ds_read_b64_tr_b16 v[138:139], v217 offset:53088
	v_mfma_f32_16x16x32_bf16 v[88:91], v[228:231], v[108:111], v[88:91]
	v_exp_f32_e32 v92, v92
	v_exp_f32_e32 v93, v93
	v_mfma_f32_16x16x32_bf16 v[84:87], v[228:231], v[112:115], v[84:87]
	v_exp_f32_e32 v94, v94
	v_exp_f32_e32 v95, v95
	s_waitcnt lgkmcnt(6)
	v_mfma_f32_16x16x32_bf16 v[80:83], v[124:127], v[108:111], v[80:83]
	v_exp_f32_e32 v100, v100
	v_exp_f32_e32 v101, v101
	v_mfma_f32_16x16x32_bf16 v[12:15], v[124:127], v[112:115], v[12:15]
	v_exp_f32_e32 v102, v102
	v_exp_f32_e32 v103, v103
	s_waitcnt lgkmcnt(4)
	v_mfma_f32_16x16x32_bf16 v[76:79], v[128:131], v[108:111], v[76:79]
	v_cvt_pk_bf16_f32 v116, v92, v93
	v_cvt_pk_bf16_f32 v117, v94, v95
	v_cvt_pk_bf16_f32 v118, v100, v101
	s_cmpk_eq_i32 s46, 0x780
	s_cbranch_scc1 .Lb2_skip3_n
	v_add_u32_e32 v219, s1, v183
	s_waitcnt vmcnt(1)
	ds_write_b128 v219, v[4:7]
	s_waitcnt vmcnt(0)
	ds_write_b128 v219, v[8:11] offset:36864
	v_add_co_u32_e32 v180, vcc, 0x4000, v180
	s_nop 1
	v_addc_co_u32_e32 v181, vcc, 0, v181, vcc
